# P4 epilogue: residual rows of groups 0-3 issued up front (2 staged in dead fragment registers), 4-7 two groups ahead, counted vmcnt per group
# baseline (speedup 1.0000x reference)
.LBB0_675:
	s_lshl_b32 s38, s4, 8
	v_add_u32_e32 v128, s38, v157
	v_ashrrev_i32_e32 v129, 31, v128
	s_lshl_b32 s6, s55, 8
	v_lshlrev_b64 v[128:129], 11, v[128:129]
	s_ashr_i32 s7, s6, 31
	v_lshl_add_u64 v[178:179], v[128:129], 0, s[6:7]
	v_or_b32_e32 v178, v178, v156
	v_lshl_add_u64 v[128:129], v[178:179], 2, s[8:9]
	global_load_dwordx4 v[162:165], v[128:129], off
	global_load_dwordx4 v[170:173], v[128:129], off offset:16
	global_load_dwordx4 v[192:195], v[128:129], off offset:512
	global_load_dwordx4 v[196:199], v[128:129], off offset:528
	v_lshl_add_u64 v[182:183], v[128:129], 0, s[16:17]
	global_load_dwordx4 v[140:143], v[182:183], off
	global_load_dwordx4 v[136:139], v[182:183], off offset:16
	global_load_dwordx4 v[132:135], v[182:183], off offset:512
	global_load_dwordx4 v[128:131], v[182:183], off offset:528
	v_lshl_add_u64 v[182:183], v[182:183], 0, s[16:17]
	global_load_dwordx4 v[200:203], v[182:183], off
	global_load_dwordx4 v[204:207], v[182:183], off offset:16
	global_load_dwordx4 v[208:211], v[182:183], off offset:512
	global_load_dwordx4 v[212:215], v[182:183], off offset:528
	v_lshl_add_u64 v[182:183], v[182:183], 0, s[16:17]
	global_load_dwordx4 v[216:219], v[182:183], off
	global_load_dwordx4 v[220:223], v[182:183], off offset:16
	global_load_dwordx4 v[224:227], v[182:183], off offset:512
	global_load_dwordx4 v[246:249], v[182:183], off offset:528
	v_and_b32_e32 v167, 64, v187
	v_xor_b32_e32 v166, 16, v187
	v_add_u32_e32 v180, 64, v167
	v_cmp_lt_i32_e32 vcc, v166, v180
	s_ashr_i32 s39, s38, 31
	s_waitcnt vmcnt(12)
	v_pk_add_f32 v[168:169], v[126:127], v[164:165]
	v_cndmask_b32_e32 v166, v187, v166, vcc
	v_lshlrev_b32_e32 v191, 2, v166
	v_pk_add_f32 v[176:177], v[124:125], v[162:163]
	v_pk_add_f32 v[166:167], v[122:123], v[172:173]
	v_pk_add_f32 v[174:175], v[120:121], v[170:171]
	v_pk_add_f32 v[164:165], v[118:119], v[194:195]
	v_pk_add_f32 v[172:173], v[116:117], v[192:193]
	v_pk_add_f32 v[162:163], v[114:115], v[198:199]
	v_pk_add_f32 v[170:171], v[112:113], v[196:197]
	v_mul_f32_e32 v112, v177, v177
	v_mul_f32_e32 v113, v169, v169
	v_mul_f32_e32 v114, v175, v175
	v_mul_f32_e32 v115, v167, v167
	v_mul_f32_e32 v116, v173, v173
	v_mul_f32_e32 v117, v165, v165
	v_fmac_f32_e32 v112, v176, v176
	v_fmac_f32_e32 v113, v168, v168
	v_fmac_f32_e32 v114, v174, v174
	v_fmac_f32_e32 v115, v166, v166
	v_mul_f32_e32 v118, v171, v171
	v_mul_f32_e32 v119, v163, v163
	v_fmac_f32_e32 v116, v172, v172
	v_fmac_f32_e32 v117, v164, v164
	v_add_f32_e32 v112, v112, v113
	v_add_f32_e32 v113, v114, v115
	v_fmac_f32_e32 v118, v170, v170
	v_fmac_f32_e32 v119, v162, v162
	v_add_f32_e32 v114, v116, v117
	v_add_f32_e32 v112, v112, v113
	v_add_f32_e32 v115, v118, v119
	v_add_f32_e32 v112, v112, v114
	v_add_f32_e32 v112, v112, v115
	ds_bpermute_b32 v113, v191, v112
	v_xor_b32_e32 v114, 32, v187
	v_cmp_lt_i32_e32 vcc, v114, v180
	v_lshl_add_u64 v[180:181], s[38:39], 2, v[152:153]
	s_waitcnt lgkmcnt(0)
	v_add_f32_e32 v112, v112, v113
	v_cndmask_b32_e32 v114, v187, v114, vcc
	v_lshlrev_b32_e32 v192, 2, v114
	ds_bpermute_b32 v113, v192, v112
	s_and_saveexec_b64 s[38:39], s[0:1]
	s_cbranch_execz .LBB0_677
	s_waitcnt lgkmcnt(0)
	v_add_f32_e32 v112, v112, v113
	global_atomic_add_f32 v[180:181], v112, off
.LBB0_677:
	s_or_b64 exec, exec, s[38:39]
	s_waitcnt vmcnt(9)
	v_pk_add_f32 v[142:143], v[110:111], v[142:143]
	v_pk_add_f32 v[140:141], v[108:109], v[140:141]
	v_pk_add_f32 v[138:139], v[106:107], v[138:139]
	s_waitcnt lgkmcnt(0)
	v_pk_add_f32 v[136:137], v[104:105], v[136:137]
	v_mul_f32_e32 v108, v141, v141
	v_mul_f32_e32 v109, v143, v143
	v_mul_f32_e32 v104, v137, v137
	v_mul_f32_e32 v105, v139, v139
	v_pk_add_f32 v[134:135], v[102:103], v[134:135]
	v_pk_add_f32 v[132:133], v[100:101], v[132:133]
	v_fmac_f32_e32 v108, v140, v140
	v_fmac_f32_e32 v109, v142, v142
	v_fmac_f32_e32 v104, v136, v136
	v_fmac_f32_e32 v105, v138, v138
	v_mul_f32_e32 v100, v133, v133
	v_mul_f32_e32 v101, v135, v135
	v_pk_add_f32 v[130:131], v[98:99], v[130:131]
	v_pk_add_f32 v[128:129], v[96:97], v[128:129]
	v_add_f32_e32 v108, v108, v109
	v_add_f32_e32 v104, v104, v105
	v_fmac_f32_e32 v100, v132, v132
	v_fmac_f32_e32 v101, v134, v134
	v_mul_f32_e32 v96, v129, v129
	v_mul_f32_e32 v97, v131, v131
	v_add_f32_e32 v104, v108, v104
	v_add_f32_e32 v100, v100, v101
	v_fmac_f32_e32 v96, v128, v128
	v_fmac_f32_e32 v97, v130, v130
	v_add_f32_e32 v100, v104, v100
	v_add_f32_e32 v96, v96, v97
	v_add_f32_e32 v96, v100, v96
	ds_bpermute_b32 v97, v191, v96
	s_waitcnt lgkmcnt(0)
	v_add_f32_e32 v96, v96, v97
	ds_bpermute_b32 v97, v192, v96
	s_and_saveexec_b64 s[38:39], s[0:1]
	s_cbranch_execz .LBB0_679
	s_waitcnt lgkmcnt(0)
	v_add_f32_e32 v96, v96, v97
	global_atomic_add_f32 v[180:181], v96, off offset:64
.LBB0_679:
	s_or_b64 exec, exec, s[38:39]
	s_waitcnt vmcnt(6)
	v_pk_add_f32 v[126:127], v[94:95], v[202:203]
	v_pk_add_f32 v[124:125], v[92:93], v[200:201]
	v_pk_add_f32 v[122:123], v[90:91], v[206:207]
	s_waitcnt lgkmcnt(0)
	v_pk_add_f32 v[120:121], v[88:89], v[204:205]
	v_mul_f32_e32 v92, v125, v125
	v_mul_f32_e32 v93, v127, v127
	v_mul_f32_e32 v88, v121, v121
	v_mul_f32_e32 v89, v123, v123
	v_pk_add_f32 v[118:119], v[86:87], v[210:211]
	v_pk_add_f32 v[116:117], v[84:85], v[208:209]
	v_fmac_f32_e32 v92, v124, v124
	v_fmac_f32_e32 v93, v126, v126
	v_fmac_f32_e32 v88, v120, v120
	v_fmac_f32_e32 v89, v122, v122
	v_mul_f32_e32 v84, v117, v117
	v_mul_f32_e32 v85, v119, v119
	v_pk_add_f32 v[114:115], v[82:83], v[214:215]
	v_pk_add_f32 v[112:113], v[80:81], v[212:213]
	v_add_f32_e32 v92, v92, v93
	v_add_f32_e32 v88, v88, v89
	v_fmac_f32_e32 v84, v116, v116
	v_fmac_f32_e32 v85, v118, v118
	v_mul_f32_e32 v80, v113, v113
	v_mul_f32_e32 v81, v115, v115
	v_add_f32_e32 v88, v92, v88
	v_add_f32_e32 v84, v84, v85
	v_fmac_f32_e32 v80, v112, v112
	v_fmac_f32_e32 v81, v114, v114
	v_add_f32_e32 v84, v88, v84
	v_add_f32_e32 v80, v80, v81
	v_add_f32_e32 v80, v84, v80
	ds_bpermute_b32 v81, v191, v80
	s_waitcnt lgkmcnt(0)
	v_add_f32_e32 v80, v80, v81
	ds_bpermute_b32 v81, v192, v80
	s_and_saveexec_b64 s[38:39], s[0:1]
	s_cbranch_execz .LBB0_681
	s_waitcnt lgkmcnt(0)
	v_add_f32_e32 v80, v80, v81
	global_atomic_add_f32 v[180:181], v80, off offset:128
.LBB0_681:
	s_or_b64 exec, exec, s[38:39]
	v_lshl_add_u64 v[182:183], v[182:183], 0, s[20:21]
	global_load_dwordx4 v[92:95], v[182:183], off
	global_load_dwordx4 v[88:91], v[182:183], off offset:16
	global_load_dwordx4 v[84:87], v[182:183], off offset:512
	global_load_dwordx4 v[80:83], v[182:183], off offset:528
	v_lshl_add_u64 v[250:251], v[182:183], 0, s[16:17]
	v_lshl_add_u64 v[250:251], v[250:251], 0, s[16:17]
	global_load_dwordx4 v[200:203], v[250:251], off
	global_load_dwordx4 v[204:207], v[250:251], off offset:16
	global_load_dwordx4 v[208:211], v[250:251], off offset:512
	global_load_dwordx4 v[212:215], v[250:251], off offset:528
	s_waitcnt vmcnt(11)
	v_pk_add_f32 v[110:111], v[78:79], v[218:219]
	v_pk_add_f32 v[108:109], v[76:77], v[216:217]
	v_pk_add_f32 v[106:107], v[74:75], v[222:223]
	s_waitcnt lgkmcnt(0)
	v_pk_add_f32 v[104:105], v[72:73], v[220:221]
	v_mul_f32_e32 v76, v109, v109
	v_mul_f32_e32 v77, v111, v111
	v_mul_f32_e32 v72, v105, v105
	v_mul_f32_e32 v73, v107, v107
	v_pk_add_f32 v[102:103], v[70:71], v[226:227]
	v_pk_add_f32 v[100:101], v[68:69], v[224:225]
	v_fmac_f32_e32 v76, v108, v108
	v_fmac_f32_e32 v77, v110, v110
	v_fmac_f32_e32 v72, v104, v104
	v_fmac_f32_e32 v73, v106, v106
	v_mul_f32_e32 v68, v101, v101
	v_mul_f32_e32 v69, v103, v103
	v_pk_add_f32 v[98:99], v[66:67], v[248:249]
	v_pk_add_f32 v[96:97], v[64:65], v[246:247]
	v_add_f32_e32 v76, v76, v77
	v_add_f32_e32 v72, v72, v73
	v_fmac_f32_e32 v68, v100, v100
	v_fmac_f32_e32 v69, v102, v102
	v_mul_f32_e32 v64, v97, v97
	v_mul_f32_e32 v65, v99, v99
	v_add_f32_e32 v72, v76, v72
	v_add_f32_e32 v68, v68, v69
	v_fmac_f32_e32 v64, v96, v96
	v_fmac_f32_e32 v65, v98, v98
	v_add_f32_e32 v68, v72, v68
	v_add_f32_e32 v64, v64, v65
	v_add_f32_e32 v64, v68, v64
	ds_bpermute_b32 v65, v191, v64
	s_waitcnt lgkmcnt(0)
	v_add_f32_e32 v64, v64, v65
	ds_bpermute_b32 v65, v192, v64
	s_and_saveexec_b64 s[38:39], s[0:1]
	s_cbranch_execz .LBB0_683
	s_waitcnt lgkmcnt(0)
	v_add_f32_e32 v64, v64, v65
	global_atomic_add_f32 v[180:181], v64, off offset:192
.LBB0_683:
	s_or_b64 exec, exec, s[38:39]
	v_lshl_add_u64 v[182:183], v[182:183], 0, s[16:17]
	global_load_dwordx4 v[76:79], v[182:183], off
	global_load_dwordx4 v[72:75], v[182:183], off offset:16
	global_load_dwordx4 v[68:71], v[182:183], off offset:512
	global_load_dwordx4 v[64:67], v[182:183], off offset:528
	v_lshl_add_u64 v[250:251], v[182:183], 0, s[16:17]
	v_lshl_add_u64 v[250:251], v[250:251], 0, s[16:17]
	global_load_dwordx4 v[216:219], v[250:251], off
	global_load_dwordx4 v[220:223], v[250:251], off offset:16
	global_load_dwordx4 v[224:227], v[250:251], off offset:512
	global_load_dwordx4 v[246:249], v[250:251], off offset:528
	s_waitcnt vmcnt(13)
	v_pk_add_f32 v[94:95], v[62:63], v[94:95]
	v_pk_add_f32 v[92:93], v[60:61], v[92:93]
	v_pk_add_f32 v[90:91], v[58:59], v[90:91]
	s_waitcnt lgkmcnt(0)
	v_pk_add_f32 v[88:89], v[56:57], v[88:89]
	v_mul_f32_e32 v60, v93, v93
	v_mul_f32_e32 v61, v95, v95
	v_mul_f32_e32 v56, v89, v89
	v_mul_f32_e32 v57, v91, v91
	v_pk_add_f32 v[86:87], v[54:55], v[86:87]
	v_pk_add_f32 v[84:85], v[52:53], v[84:85]
	v_fmac_f32_e32 v60, v92, v92
	v_fmac_f32_e32 v61, v94, v94
	v_fmac_f32_e32 v56, v88, v88
	v_fmac_f32_e32 v57, v90, v90
	v_mul_f32_e32 v52, v85, v85
	v_mul_f32_e32 v53, v87, v87
	v_pk_add_f32 v[82:83], v[50:51], v[82:83]
	v_pk_add_f32 v[80:81], v[48:49], v[80:81]
	v_add_f32_e32 v60, v60, v61
	v_add_f32_e32 v56, v56, v57
	v_fmac_f32_e32 v52, v84, v84
	v_fmac_f32_e32 v53, v86, v86
	v_mul_f32_e32 v48, v81, v81
	v_mul_f32_e32 v49, v83, v83
	v_add_f32_e32 v56, v60, v56
	v_add_f32_e32 v52, v52, v53
	v_fmac_f32_e32 v48, v80, v80
	v_fmac_f32_e32 v49, v82, v82
	v_add_f32_e32 v52, v56, v52
	v_add_f32_e32 v48, v48, v49
	v_add_f32_e32 v48, v52, v48
	ds_bpermute_b32 v49, v191, v48
	s_waitcnt lgkmcnt(0)
	v_add_f32_e32 v48, v48, v49
	ds_bpermute_b32 v49, v192, v48
	s_and_saveexec_b64 s[38:39], s[0:1]
	s_cbranch_execz .LBB0_685
	s_waitcnt lgkmcnt(0)
	v_add_f32_e32 v48, v48, v49
	global_atomic_add_f32 v[180:181], v48, off offset:512
.LBB0_685:
	s_or_b64 exec, exec, s[38:39]
	s_waitcnt vmcnt(5)
	v_pk_add_f32 v[78:79], v[46:47], v[78:79]
	v_pk_add_f32 v[76:77], v[44:45], v[76:77]
	v_pk_add_f32 v[74:75], v[42:43], v[74:75]
	s_waitcnt lgkmcnt(0)
	v_pk_add_f32 v[72:73], v[40:41], v[72:73]
	v_mul_f32_e32 v44, v77, v77
	v_mul_f32_e32 v45, v79, v79
	v_mul_f32_e32 v40, v73, v73
	v_mul_f32_e32 v41, v75, v75
	v_pk_add_f32 v[70:71], v[38:39], v[70:71]
	v_pk_add_f32 v[68:69], v[36:37], v[68:69]
	v_fmac_f32_e32 v44, v76, v76
	v_fmac_f32_e32 v45, v78, v78
	v_fmac_f32_e32 v40, v72, v72
	v_fmac_f32_e32 v41, v74, v74
	v_mul_f32_e32 v36, v69, v69
	v_mul_f32_e32 v37, v71, v71
	v_pk_add_f32 v[66:67], v[34:35], v[66:67]
	v_pk_add_f32 v[64:65], v[32:33], v[64:65]
	v_add_f32_e32 v44, v44, v45
	v_add_f32_e32 v40, v40, v41
	v_fmac_f32_e32 v36, v68, v68
	v_fmac_f32_e32 v37, v70, v70
	v_mul_f32_e32 v32, v65, v65
	v_mul_f32_e32 v33, v67, v67
	v_add_f32_e32 v40, v44, v40
	v_add_f32_e32 v36, v36, v37
	v_fmac_f32_e32 v32, v64, v64
	v_fmac_f32_e32 v33, v66, v66
	v_add_f32_e32 v36, v40, v36
	v_add_f32_e32 v32, v32, v33
	v_add_f32_e32 v32, v36, v32
	ds_bpermute_b32 v33, v191, v32
	s_waitcnt lgkmcnt(0)
	v_add_f32_e32 v32, v32, v33
	ds_bpermute_b32 v33, v192, v32
	s_and_saveexec_b64 s[38:39], s[0:1]
	s_cbranch_execz .LBB0_687
	s_waitcnt lgkmcnt(0)
	v_add_f32_e32 v32, v32, v33
	global_atomic_add_f32 v[180:181], v32, off offset:576
.LBB0_687:
	s_or_b64 exec, exec, s[38:39]
	s_waitcnt vmcnt(11)
	v_pk_add_f32 v[62:63], v[30:31], v[202:203]
	v_pk_add_f32 v[60:61], v[28:29], v[200:201]
	v_pk_add_f32 v[58:59], v[26:27], v[206:207]
	s_waitcnt lgkmcnt(0)
	v_pk_add_f32 v[56:57], v[24:25], v[204:205]
	v_mul_f32_e32 v28, v61, v61
	v_mul_f32_e32 v29, v63, v63
	v_mul_f32_e32 v24, v57, v57
	v_mul_f32_e32 v25, v59, v59
	v_pk_add_f32 v[54:55], v[22:23], v[210:211]
	v_pk_add_f32 v[52:53], v[20:21], v[208:209]
	v_fmac_f32_e32 v28, v60, v60
	v_fmac_f32_e32 v29, v62, v62
	v_fmac_f32_e32 v24, v56, v56
	v_fmac_f32_e32 v25, v58, v58
	v_mul_f32_e32 v20, v53, v53
	v_mul_f32_e32 v21, v55, v55
	v_add_f32_e32 v28, v28, v29
	v_add_f32_e32 v24, v24, v25
	v_fmac_f32_e32 v20, v52, v52
	v_fmac_f32_e32 v21, v54, v54
	v_add_f32_e32 v24, v28, v24
	v_add_f32_e32 v20, v20, v21
	v_add_f32_e32 v20, v24, v20
	v_pk_add_f32 v[24:25], v[18:19], v[214:215]
	v_pk_add_f32 v[48:49], v[16:17], v[212:213]
	v_mul_f32_e32 v17, v25, v25
	v_mul_f32_e32 v16, v49, v49
	v_fmac_f32_e32 v16, v48, v48
	v_fmac_f32_e32 v17, v24, v24
	v_add_f32_e32 v16, v16, v17
	v_add_f32_e32 v16, v20, v16
	ds_bpermute_b32 v17, v191, v16
	s_waitcnt lgkmcnt(0)
	v_add_f32_e32 v16, v16, v17
	ds_bpermute_b32 v17, v192, v16
	s_and_saveexec_b64 s[38:39], s[0:1]
	s_cbranch_execz .LBB0_689
	s_waitcnt lgkmcnt(0)
	v_add_f32_e32 v16, v16, v17
	global_atomic_add_f32 v[180:181], v16, off offset:640
.LBB0_689:
	s_or_b64 exec, exec, s[38:39]
	s_waitcnt vmcnt(3) lgkmcnt(0)
	v_pk_add_f32 v[16:17], v[14:15], v[218:219]
	v_pk_add_f32 v[20:21], v[12:13], v[216:217]
	v_pk_add_f32 v[18:19], v[10:11], v[222:223]
	v_pk_add_f32 v[26:27], v[8:9], v[220:221]
	v_mul_f32_e32 v12, v21, v21
	v_mul_f32_e32 v13, v17, v17
	v_mul_f32_e32 v8, v27, v27
	v_mul_f32_e32 v9, v19, v19
	v_pk_add_f32 v[22:23], v[6:7], v[226:227]
	v_pk_add_f32 v[30:31], v[4:5], v[224:225]
	v_fmac_f32_e32 v12, v20, v20
	v_fmac_f32_e32 v13, v16, v16
	v_fmac_f32_e32 v8, v26, v26
	v_fmac_f32_e32 v9, v18, v18
	v_mul_f32_e32 v4, v31, v31
	v_mul_f32_e32 v5, v23, v23
	v_pk_add_f32 v[28:29], v[2:3], v[248:249]
	v_pk_add_f32 v[32:33], v[0:1], v[246:247]
	v_add_f32_e32 v12, v12, v13
	v_add_f32_e32 v8, v8, v9
	v_fmac_f32_e32 v4, v30, v30
	v_fmac_f32_e32 v5, v22, v22
	v_mul_f32_e32 v0, v33, v33
	v_mul_f32_e32 v1, v29, v29
	v_add_f32_e32 v8, v12, v8
	v_add_f32_e32 v4, v4, v5
	v_fmac_f32_e32 v0, v32, v32
	v_fmac_f32_e32 v1, v28, v28
	v_add_f32_e32 v4, v8, v4
	v_add_f32_e32 v0, v0, v1
	v_add_f32_e32 v0, v4, v0
	ds_bpermute_b32 v1, v191, v0
	v_lshl_add_u64 v[2:3], v[182:183], 0, s[20:21]
	s_waitcnt lgkmcnt(0)
	v_add_f32_e32 v0, v0, v1
	ds_bpermute_b32 v1, v192, v0
	s_and_saveexec_b64 s[38:39], s[0:1]
	s_cbranch_execz .LBB0_691
	s_waitcnt lgkmcnt(0)
	v_add_f32_e32 v0, v0, v1
	global_atomic_add_f32 v[180:181], v0, off offset:704
